# attention work queues: next unit ticket prefetched with a returning atomic kept in flight during the current unit (on top of v66)
# baseline (speedup 1.0000x reference)
.LBB0_289:
	s_or_b64 exec, exec, s[4:5]
	s_mov_b32 s67, s89
	s_lshl_b64 s[4:5], s[66:67], 2
	v_readlane_b32 s6, v255, 17
	s_add_u32 s34, s76, s4
	v_readlane_b32 s7, v255, 18
	s_addc_u32 s35, s77, s5
	s_mov_b64 s[4:5], -1
	s_and_b64 vcc, exec, s[6:7]
	s_cbranch_vccz .LBB0_417
	v_mov_b32_e32 v2, v202
	v_readlane_b32 s56, v252, 23
	v_readlane_b32 s57, v252, 24
	v_ashrrev_i32_e32 v3, 31, v2
	v_mbcnt_hi_u32_b32 v6, -1, v209
	v_lshl_add_u64 v[2:3], v[2:3], 2, s[56:57]
	global_load_dword v1, v[2:3], off
	global_load_dword v4, v[2:3], off offset:256
	v_and_b32_e32 v7, 64, v6
	v_add_u32_e32 v7, 64, v7
	v_xor_b32_e32 v8, 1, v6
	v_cmp_lt_i32_e32 vcc, v8, v7
	s_mov_b32 s4, 0x3fb8aa3b
	s_mov_b32 s5, 0xc2ce8ed0
	v_cndmask_b32_e32 v8, v6, v8, vcc
	v_lshlrev_b32_e32 v8, 2, v8
	s_mov_b32 s6, 0x42b17218
	v_readlane_b32 s63, v252, 30
	v_readlane_b32 s63, v254, 44
	v_readlane_b32 s58, v252, 25
	v_readlane_b32 s59, v252, 26
	v_readlane_b32 s60, v252, 27
	v_readlane_b32 s61, v252, 28
	v_readlane_b32 s62, v252, 29
	v_readlane_b32 s64, v252, 31
	v_readlane_b32 s65, v252, 32
	v_readlane_b32 s66, v252, 33
	v_readlane_b32 s67, v252, 34
	v_readlane_b32 s68, v252, 35
	v_readlane_b32 s69, v252, 36
	v_readlane_b32 s70, v252, 37
	v_readlane_b32 s71, v252, 38
	s_waitcnt vmcnt(0)
	v_mul_f32_e32 v5, v1, v4
	ds_bpermute_b32 v5, v8, v5
	s_waitcnt lgkmcnt(0)
	v_fmac_f32_e32 v5, v1, v4
	v_xor_b32_e32 v1, 2, v6
	v_cmp_lt_i32_e32 vcc, v1, v7
	s_nop 1
	v_cndmask_b32_e32 v1, v6, v1, vcc
	v_lshlrev_b32_e32 v1, 2, v1
	ds_bpermute_b32 v4, v1, v5
	s_waitcnt lgkmcnt(0)
	v_add_f32_e32 v4, v5, v4
	v_xor_b32_e32 v5, 4, v6
	v_cmp_lt_i32_e32 vcc, v5, v7
	s_nop 1
	v_cndmask_b32_e32 v5, v6, v5, vcc
	v_lshlrev_b32_e32 v5, 2, v5
	ds_bpermute_b32 v9, v5, v4
	s_waitcnt lgkmcnt(0)
	v_add_f32_e32 v4, v4, v9
	v_xor_b32_e32 v9, 8, v6
	v_cmp_lt_i32_e32 vcc, v9, v7
	s_nop 1
	v_cndmask_b32_e32 v9, v6, v9, vcc
	v_lshlrev_b32_e32 v9, 2, v9
	ds_bpermute_b32 v10, v9, v4
	s_waitcnt lgkmcnt(0)
	v_add_f32_e32 v4, v4, v10
	v_xor_b32_e32 v10, 16, v6
	v_cmp_lt_i32_e32 vcc, v10, v7
	s_nop 1
	v_cndmask_b32_e32 v10, v6, v10, vcc
	v_lshlrev_b32_e32 v10, 2, v10
	ds_bpermute_b32 v11, v10, v4
	s_waitcnt lgkmcnt(0)
	v_add_f32_e32 v4, v4, v11
	v_xor_b32_e32 v11, 32, v6
	v_cmp_lt_i32_e32 vcc, v11, v7
	s_nop 1
	v_cndmask_b32_e32 v6, v6, v11, vcc
	v_lshlrev_b32_e32 v200, 2, v6
	ds_bpermute_b32 v6, v200, v4
	s_waitcnt lgkmcnt(0)
	v_add_f32_e32 v4, v4, v6
	global_load_dword v6, v[2:3], off offset:512
	s_nop 0
	global_load_dword v2, v[2:3], off offset:768
	v_cmp_ngt_f32_e32 vcc, s5, v4
	s_waitcnt vmcnt(0)
	v_mul_f32_e32 v3, v6, v2
	ds_bpermute_b32 v3, v8, v3
	s_waitcnt lgkmcnt(0)
	v_fmac_f32_e32 v3, v6, v2
	ds_bpermute_b32 v1, v1, v3
	v_mov_b32_e32 v6, 0x7f800000
	s_waitcnt lgkmcnt(0)
	v_add_f32_e32 v1, v3, v1
	ds_bpermute_b32 v2, v5, v1
	s_waitcnt lgkmcnt(0)
	v_add_f32_e32 v1, v1, v2
	ds_bpermute_b32 v2, v9, v1
	s_waitcnt lgkmcnt(0)
	v_add_f32_e32 v1, v1, v2
	ds_bpermute_b32 v2, v10, v1
	s_waitcnt lgkmcnt(0)
	v_add_f32_e32 v1, v1, v2
	ds_bpermute_b32 v2, v200, v1
	s_waitcnt lgkmcnt(0)
	v_add_f32_e32 v1, v1, v2
	v_mul_f32_e32 v2, 0x3fb8aa3b, v4
	v_fma_f32 v3, v4, s4, -v2
	v_rndne_f32_e32 v5, v2
	v_fmac_f32_e32 v3, 0x32a5705f, v4
	v_sub_f32_e32 v2, v2, v5
	v_add_f32_e32 v2, v2, v3
	v_exp_f32_e32 v2, v2
	v_cvt_i32_f32_e32 v3, v5
	v_ldexp_f32 v2, v2, v3
	v_mul_f32_e32 v3, 0x3fb8aa3b, v1
	v_cndmask_b32_e32 v2, 0, v2, vcc
	v_cmp_nlt_f32_e32 vcc, s6, v4
	v_fma_f32 v4, v1, s4, -v3
	v_rndne_f32_e32 v5, v3
	v_fmac_f32_e32 v4, 0x32a5705f, v1
	v_sub_f32_e32 v3, v3, v5
	v_add_f32_e32 v3, v3, v4
	v_exp_f32_e32 v3, v3
	v_cvt_i32_f32_e32 v4, v5
	v_cndmask_b32_e32 v2, v6, v2, vcc
	v_cmp_ngt_f32_e32 vcc, s5, v1
	v_ldexp_f32 v3, v3, v4
	s_nop 0
	v_cndmask_b32_e32 v3, 0, v3, vcc
	v_cmp_nlt_f32_e32 vcc, s6, v1
	s_nop 1
	v_cndmask_b32_e32 v1, v6, v3, vcc
	v_sub_f32_e32 v1, v2, v1
	v_add_f32_e32 v184, 0x3eb60549, v1
	v_mov_b32_e32 v185, v184
	s_and_saveexec_b64 s[4:5], s[0:1]
	v_mov_b32_e32 v250, 1
	s_cbranch_execz .Lpf_l1
	global_atomic_add v250, v0, v250, s[34:35] sc0
.Lpf_l1:
	s_or_b64 exec, exec, s[4:5]
	s_branch .LBB0_294

.LBB0_294:
	s_barrier
	s_and_saveexec_b64 s[4:5], s[0:1]
	s_cbranch_execz .LBB0_298
	s_waitcnt vmcnt(0)
	v_readfirstlane_b32 s6, v250
	v_mov_b32_e32 v250, 1
	global_atomic_add v250, v0, v250, s[34:35] sc0
	v_mov_b32_e32 v2, s33
	v_mov_b32_e32 v1, s6
	ds_write_b32 v2, v1

.Lpf_l0_entry:
	s_and_saveexec_b64 s[4:5], s[0:1]
	v_mov_b32_e32 v250, 1
	s_cbranch_execz .Lpf_l0
	global_atomic_add v250, v0, v250, s[34:35] sc0

.LBB0_424:
	s_waitcnt vmcnt(0)
	s_barrier
	s_and_saveexec_b64 s[4:5], s[0:1]
	s_cbranch_execz .LBB0_428
	s_waitcnt vmcnt(0)
	v_readfirstlane_b32 s6, v250
	v_mov_b32_e32 v250, 1
	global_atomic_add v250, v0, v250, s[34:35] sc0
	v_mov_b32_e32 v2, s33
	v_mov_b32_e32 v1, s6
	ds_write_b32 v2, v1
